# attention PV: V fragments read with ds_read_b64 directly into MFMA operand registers (no v_mov shuffles), 7 of 13 tile bodies
# speedup vs baseline: 1.0121x; 1.0096x over previous
; template <int DK, int MODE, int RBM, class SF, class FF, class POST>
; DEVI void attn_tile_body(const bf16x8 (&qf)[2][DK / 32], const char* Ks, const char* Vs, SF& sf, FF& ff, POST& post,
;                          int cur, int c0, int c1, float (&m)[2], float (&l)[2], f32x4 (&o)[5][2], int fr, int fq) {
;     ...
;     bf16x8 pf[2][2];
; #pragma unroll
;     for (int rb = 0; rb < 2; ++rb) {
;       if (!(RBM & (1 << rb))) continue;
; #pragma unroll
;       for (int kp2 = 0; kp2 < 2; ++kp2) {
;         u32x4 w;
;         w[0] = pack2(s[2 * kp2][rb][0], s[2 * kp2][rb][1]); w[1] = pack2(s[2 * kp2][rb][2], s[2 * kp2][rb][3]);
;         w[2] = pack2(s[2 * kp2 + 1][rb][0], s[2 * kp2 + 1][rb][1]); w[3] = pack2(s[2 * kp2 + 1][rb][2], s[2 * kp2 + 1][rb][3]);
;         pf[rb][kp2] = __builtin_bit_cast(bf16x8, w);
;       }
;     }
; #pragma unroll
;     for (int kp2 = 0; kp2 < 2; ++kp2)
; #pragma unroll
;       for (int db = 0; db < 4; ++db) {
;         const char* base = Vs + (db * 16 + fr) * 128 + (fq & 1) * 8;
;         const int c = kp2 * 4 + (fq >> 1);
;         u32x2 lo = *(const u32x2*)(base + ((c ^ (fr & 7)) * 16));
;         u32x2 hi = *(const u32x2*)(base + (((c + 2) ^ (fr & 7)) * 16));
;         u32x4 w; w[0] = lo[0]; w[1] = lo[1]; w[2] = hi[0]; w[3] = hi[1];
;         bf16x8 vf = __builtin_bit_cast(bf16x8, w);
;         if (RBM & 1) o[db][0] = __builtin_amdgcn_mfma_f32_16x16x32_bf16(vf, pf[0][kp2], o[db][0], 0, 0, 0);
;         if (RBM & 2) o[db][1] = __builtin_amdgcn_mfma_f32_16x16x32_bf16(vf, pf[1][kp2], o[db][1], 0, 0, 0);
;       }
;     if (MODE == 0) {
;       u32x4 w1; w1[0] = w1[1] = w1[2] = w1[3] = 0x3F803F80u;
;       const bf16x8 ones = __builtin_bit_cast(bf16x8, w1);
; #pragma unroll
;       for (int kp2 = 0; kp2 < 2; ++kp2) {
;         if (RBM & 1) o[4][0] = __builtin_amdgcn_mfma_f32_16x16x32_bf16(ones, pf[0][kp2], o[4][0], 0, 0, 0);
;         if (RBM & 2) o[4][1] = __builtin_amdgcn_mfma_f32_16x16x32_bf16(ones, pf[1][kp2], o[4][1], 0, 0, 0);
;       }
.LBB0_528:
	s_or_b64 exec, exec, s[94:95]
	v_exp_f32_e32 v2, v195
	v_exp_f32_e32 v3, v95
	v_cvt_pk_bf16_f32 v68, v80, v81
	v_cvt_pk_bf16_f32 v71, v86, v88
	v_cvt_pk_bf16_f32 v67, v194, v2
	v_add3_u32 v2, s6, v135, v115
	v_cvt_pk_bf16_f32 v75, v94, v3
	v_add_u32_e32 v3, v2, v136
	v_add_u32_e32 v80, v2, v137
	v_add_u32_e32 v3, 0x100, v3
	v_add_u32_e32 v88, 0x100, v80
	v_cvt_pk_bf16_f32 v60, v76, v144
	v_cvt_pk_bf16_f32 v69, v82, v83
	ds_read_b64 v[232:233], v3 offset:24576
	ds_read_b64 v[236:237], v3 offset:26624
	ds_read_b64 v[234:235], v88 offset:24576
	ds_read_b64 v[238:239], v88 offset:26624
	v_cvt_pk_bf16_f32 v72, v87, v89
	v_cvt_pk_bf16_f32 v61, v145, v146
	v_cvt_pk_bf16_f32 v62, v147, v148
	v_cvt_pk_bf16_f32 v63, v149, v151
	s_waitcnt lgkmcnt(0)
	v_cvt_pk_bf16_f32 v70, v84, v85
	v_mfma_f32_16x16x32_bf16 v[52:55], v[236:239], v[60:63], v[52:55]
	v_cvt_pk_bf16_f32 v64, v150, v152
	v_cvt_pk_bf16_f32 v65, v153, v191
	v_cvt_pk_bf16_f32 v66, v192, v193
	v_mfma_f32_16x16x32_bf16 v[36:39], v[236:239], v[68:71], v[36:39]
	ds_read_b64 v[240:241], v3 offset:28672
	ds_read_b64 v[244:245], v3 offset:30720
	ds_read_b64 v[242:243], v88 offset:28672
	ds_read_b64 v[246:247], v88 offset:30720
	v_add_u32_e32 v3, v2, v138
	v_add_u32_e32 v2, v2, v139
	v_mfma_f32_16x16x32_bf16 v[56:59], v[232:235], v[60:63], v[56:59]
	v_add_u32_e32 v3, 0x100, v3
	v_add_u32_e32 v2, 0x100, v2
	v_cvt_pk_bf16_f32 v73, v90, v91
	v_mfma_f32_16x16x32_bf16 v[40:43], v[232:235], v[68:71], v[40:43]
	s_waitcnt lgkmcnt(0)
	v_mfma_f32_16x16x32_bf16 v[44:47], v[244:247], v[60:63], v[44:47]
	ds_read_b64 v[232:233], v3 offset:24576
	ds_read_b64 v[236:237], v3 offset:26624
	v_cvt_pk_bf16_f32 v74, v92, v93
	s_mov_b32 s93, s92
	v_mfma_f32_16x16x32_bf16 v[28:31], v[244:247], v[68:71], v[28:31]
	ds_read_b64 v[234:235], v2 offset:24576
	ds_read_b64 v[238:239], v2 offset:26624
	s_mov_b32 s94, s92
	s_mov_b32 s95, s92
	v_mfma_f32_16x16x32_bf16 v[48:51], v[240:243], v[60:63], v[48:51]
	v_mfma_f32_16x16x32_bf16 v[32:35], v[240:243], v[68:71], v[32:35]
	s_waitcnt lgkmcnt(0)
	v_mfma_f32_16x16x32_bf16 v[52:55], v[236:239], v[64:67], v[52:55]
	v_mfma_f32_16x16x32_bf16 v[36:39], v[236:239], v[72:75], v[36:39]
	ds_read_b64 v[240:241], v3 offset:28672
	ds_read_b64 v[244:245], v3 offset:30720
	ds_read_b64 v[242:243], v2 offset:28672
	ds_read_b64 v[246:247], v2 offset:30720
	v_mfma_f32_16x16x32_bf16 v[56:59], v[232:235], v[64:67], v[56:59]
	v_mfma_f32_16x16x32_bf16 v[40:43], v[232:235], v[72:75], v[40:43]
	s_waitcnt lgkmcnt(0)
	v_mov_b64_e32 v[76:77], s[92:93]
	v_mov_b64_e32 v[78:79], s[94:95]
	v_mfma_f32_16x16x32_bf16 v[48:51], v[240:243], v[64:67], v[48:51]
	s_nop 0
	v_mfma_f32_16x16x32_bf16 v[24:27], v[76:79], v[60:63], v[24:27]
	v_mfma_f32_16x16x32_bf16 v[20:23], v[76:79], v[68:71], v[20:23]
	v_mfma_f32_16x16x32_bf16 v[32:35], v[240:243], v[72:75], v[32:35]
	v_mfma_f32_16x16x32_bf16 v[44:47], v[244:247], v[64:67], v[44:47]
	v_mfma_f32_16x16x32_bf16 v[28:31], v[244:247], v[72:75], v[28:31]
	v_mfma_f32_16x16x32_bf16 v[24:27], v[76:79], v[64:67], v[24:27]
	v_mfma_f32_16x16x32_bf16 v[20:23], v[76:79], v[72:75], v[20:23]

; template <int DK, int MODE, int RBM, class SF, class FF, class POST>
; DEVI void attn_tile_body(const bf16x8 (&qf)[2][DK / 32], const char* Ks, const char* Vs, SF& sf, FF& ff, POST& post,
;                          int cur, int c0, int c1, float (&m)[2], float (&l)[2], f32x4 (&o)[5][2], int fr, int fq) {
;     ...
;     bf16x8 pf[2][2];
; #pragma unroll
;     for (int rb = 0; rb < 2; ++rb) {
;       if (!(RBM & (1 << rb))) continue;
; #pragma unroll
;       for (int kp2 = 0; kp2 < 2; ++kp2) {
;         u32x4 w;
;         w[0] = pack2(s[2 * kp2][rb][0], s[2 * kp2][rb][1]); w[1] = pack2(s[2 * kp2][rb][2], s[2 * kp2][rb][3]);
;         w[2] = pack2(s[2 * kp2 + 1][rb][0], s[2 * kp2 + 1][rb][1]); w[3] = pack2(s[2 * kp2 + 1][rb][2], s[2 * kp2 + 1][rb][3]);
;         pf[rb][kp2] = __builtin_bit_cast(bf16x8, w);
;       }
;     }
; #pragma unroll
;     for (int kp2 = 0; kp2 < 2; ++kp2)
; #pragma unroll
;       for (int db = 0; db < 4; ++db) {
;         const char* base = Vs + (db * 16 + fr) * 128 + (fq & 1) * 8;
;         const int c = kp2 * 4 + (fq >> 1);
;         u32x2 lo = *(const u32x2*)(base + ((c ^ (fr & 7)) * 16));
;         u32x2 hi = *(const u32x2*)(base + (((c + 2) ^ (fr & 7)) * 16));
;         u32x4 w; w[0] = lo[0]; w[1] = lo[1]; w[2] = hi[0]; w[3] = hi[1];
;         bf16x8 vf = __builtin_bit_cast(bf16x8, w);
;         if (RBM & 1) o[db][0] = __builtin_amdgcn_mfma_f32_16x16x32_bf16(vf, pf[0][kp2], o[db][0], 0, 0, 0);
;         if (RBM & 2) o[db][1] = __builtin_amdgcn_mfma_f32_16x16x32_bf16(vf, pf[1][kp2], o[db][1], 0, 0, 0);
;       }
;     if (MODE == 0) {
;       u32x4 w1; w1[0] = w1[1] = w1[2] = w1[3] = 0x3F803F80u;
;       const bf16x8 ones = __builtin_bit_cast(bf16x8, w1);
; #pragma unroll
;       for (int kp2 = 0; kp2 < 2; ++kp2) {
;         if (RBM & 1) o[4][0] = __builtin_amdgcn_mfma_f32_16x16x32_bf16(ones, pf[0][kp2], o[4][0], 0, 0, 0);
;         if (RBM & 2) o[4][1] = __builtin_amdgcn_mfma_f32_16x16x32_bf16(ones, pf[1][kp2], o[4][1], 0, 0, 0);
;       }
.LBB0_556:
	s_or_b64 exec, exec, s[54:55]
	v_exp_f32_e32 v2, v196
	v_exp_f32_e32 v3, v95
	v_cvt_pk_bf16_f32 v71, v86, v88
	v_cvt_pk_bf16_f32 v60, v76, v145
	v_cvt_pk_bf16_f32 v67, v195, v2
	v_add3_u32 v2, s6, v135, v115
	v_cvt_pk_bf16_f32 v75, v94, v3
	v_add_u32_e32 v3, v2, v136
	v_add_u32_e32 v88, v2, v137
	v_cvt_pk_bf16_f32 v68, v80, v81
	v_cvt_pk_bf16_f32 v69, v82, v83
	ds_read_b64 v[232:233], v3 offset:8192
	ds_read_b64 v[236:237], v3 offset:10240
	ds_read_b64 v[234:235], v88 offset:8192
	ds_read_b64 v[238:239], v88 offset:10240
	v_cvt_pk_bf16_f32 v72, v87, v89
	v_cvt_pk_bf16_f32 v61, v146, v147
	v_cvt_pk_bf16_f32 v62, v148, v149
	v_cvt_pk_bf16_f32 v63, v150, v152
	s_waitcnt lgkmcnt(0)
	v_cvt_pk_bf16_f32 v70, v84, v85
	v_mfma_f32_16x16x32_bf16 v[52:55], v[236:239], v[60:63], v[52:55]
	v_cvt_pk_bf16_f32 v64, v151, v153
	v_cvt_pk_bf16_f32 v65, v191, v192
	v_cvt_pk_bf16_f32 v66, v193, v194
	v_mfma_f32_16x16x32_bf16 v[36:39], v[236:239], v[68:71], v[36:39]
	ds_read_b64 v[240:241], v3 offset:12288
	ds_read_b64 v[244:245], v3 offset:14336
	ds_read_b64 v[242:243], v88 offset:12288
	ds_read_b64 v[246:247], v88 offset:14336
	v_add_u32_e32 v3, v2, v138
	v_add_u32_e32 v2, v2, v139
	v_mfma_f32_16x16x32_bf16 v[56:59], v[232:235], v[60:63], v[56:59]
	v_cvt_pk_bf16_f32 v73, v90, v91
	v_cvt_pk_bf16_f32 v74, v92, v93
	s_mov_b32 s93, s92
	v_mfma_f32_16x16x32_bf16 v[40:43], v[232:235], v[68:71], v[40:43]
	s_waitcnt lgkmcnt(0)
	v_mfma_f32_16x16x32_bf16 v[44:47], v[244:247], v[60:63], v[44:47]
	ds_read_b64 v[232:233], v3 offset:8192
	ds_read_b64 v[236:237], v3 offset:10240
	s_mov_b32 s94, s92
	s_mov_b32 s95, s92
	v_mfma_f32_16x16x32_bf16 v[28:31], v[244:247], v[68:71], v[28:31]
	ds_read_b64 v[234:235], v2 offset:8192
	ds_read_b64 v[238:239], v2 offset:10240
	v_mfma_f32_16x16x32_bf16 v[48:51], v[240:243], v[60:63], v[48:51]
	v_mfma_f32_16x16x32_bf16 v[32:35], v[240:243], v[68:71], v[32:35]
	s_waitcnt lgkmcnt(0)
	v_mfma_f32_16x16x32_bf16 v[52:55], v[236:239], v[64:67], v[52:55]
	v_mfma_f32_16x16x32_bf16 v[36:39], v[236:239], v[72:75], v[36:39]
	ds_read_b64 v[240:241], v3 offset:12288
	ds_read_b64 v[244:245], v3 offset:14336
	ds_read_b64 v[242:243], v2 offset:12288
	ds_read_b64 v[246:247], v2 offset:14336
	v_mfma_f32_16x16x32_bf16 v[56:59], v[232:235], v[64:67], v[56:59]
	v_mfma_f32_16x16x32_bf16 v[40:43], v[232:235], v[72:75], v[40:43]
	s_waitcnt lgkmcnt(0)
	v_mov_b64_e32 v[76:77], s[92:93]
	v_mov_b64_e32 v[78:79], s[94:95]
	v_mfma_f32_16x16x32_bf16 v[48:51], v[240:243], v[64:67], v[48:51]
	s_nop 0
	v_mfma_f32_16x16x32_bf16 v[24:27], v[76:79], v[60:63], v[24:27]
	v_mfma_f32_16x16x32_bf16 v[20:23], v[76:79], v[68:71], v[20:23]
	v_mfma_f32_16x16x32_bf16 v[32:35], v[240:243], v[72:75], v[32:35]
	v_mfma_f32_16x16x32_bf16 v[44:47], v[244:247], v[64:67], v[44:47]
	v_mfma_f32_16x16x32_bf16 v[28:31], v[244:247], v[72:75], v[28:31]
	v_mfma_f32_16x16x32_bf16 v[24:27], v[76:79], v[64:67], v[24:27]
	v_mfma_f32_16x16x32_bf16 v[20:23], v[76:79], v[72:75], v[20:23]

; template <int DK, int MODE, int RBM, class SF, class FF, class POST>
; DEVI void attn_tile_body(const bf16x8 (&qf)[2][DK / 32], const char* Ks, const char* Vs, SF& sf, FF& ff, POST& post,
;                          int cur, int c0, int c1, float (&m)[2], float (&l)[2], f32x4 (&o)[5][2], int fr, int fq) {
;     ...
;     bf16x8 pf[2][2];
; #pragma unroll
;     for (int rb = 0; rb < 2; ++rb) {
;       if (!(RBM & (1 << rb))) continue;
; #pragma unroll
;       for (int kp2 = 0; kp2 < 2; ++kp2) {
;         u32x4 w;
;         w[0] = pack2(s[2 * kp2][rb][0], s[2 * kp2][rb][1]); w[1] = pack2(s[2 * kp2][rb][2], s[2 * kp2][rb][3]);
;         w[2] = pack2(s[2 * kp2 + 1][rb][0], s[2 * kp2 + 1][rb][1]); w[3] = pack2(s[2 * kp2 + 1][rb][2], s[2 * kp2 + 1][rb][3]);
;         pf[rb][kp2] = __builtin_bit_cast(bf16x8, w);
;       }
;     }
; #pragma unroll
;     for (int kp2 = 0; kp2 < 2; ++kp2)
; #pragma unroll
;       for (int db = 0; db < 4; ++db) {
;         const char* base = Vs + (db * 16 + fr) * 128 + (fq & 1) * 8;
;         const int c = kp2 * 4 + (fq >> 1);
;         u32x2 lo = *(const u32x2*)(base + ((c ^ (fr & 7)) * 16));
;         u32x2 hi = *(const u32x2*)(base + (((c + 2) ^ (fr & 7)) * 16));
;         u32x4 w; w[0] = lo[0]; w[1] = lo[1]; w[2] = hi[0]; w[3] = hi[1];
;         bf16x8 vf = __builtin_bit_cast(bf16x8, w);
;         if (RBM & 1) o[db][0] = __builtin_amdgcn_mfma_f32_16x16x32_bf16(vf, pf[0][kp2], o[db][0], 0, 0, 0);
;         if (RBM & 2) o[db][1] = __builtin_amdgcn_mfma_f32_16x16x32_bf16(vf, pf[1][kp2], o[db][1], 0, 0, 0);
;       }
;     if (MODE == 0) {
;       u32x4 w1; w1[0] = w1[1] = w1[2] = w1[3] = 0x3F803F80u;
;       const bf16x8 ones = __builtin_bit_cast(bf16x8, w1);
; #pragma unroll
;       for (int kp2 = 0; kp2 < 2; ++kp2) {
;         if (RBM & 1) o[4][0] = __builtin_amdgcn_mfma_f32_16x16x32_bf16(ones, pf[0][kp2], o[4][0], 0, 0, 0);
;         if (RBM & 2) o[4][1] = __builtin_amdgcn_mfma_f32_16x16x32_bf16(ones, pf[1][kp2], o[4][1], 0, 0, 0);
;       }
.LBB0_584:
	s_or_b64 exec, exec, s[54:55]
	v_cvt_pk_bf16_f32 v66, v0, v143
	v_add3_u32 v0, s6, v132, v131
	v_cvt_pk_bf16_f32 v79, v93, v94
	v_cvt_pk_bf16_f32 v80, v95, v96
	v_add_u32_e32 v94, v0, v133
	v_add_u32_e32 v95, v0, v134
	v_cvt_pk_bf16_f32 v74, v82, v83
	v_cvt_pk_bf16_f32 v75, v84, v85
	v_cvt_pk_bf16_f32 v76, v86, v87
	v_cvt_pk_bf16_f32 v77, v88, v90
	v_cvt_pk_bf16_f32 v78, v89, v92
	ds_read_b64 v[232:233], v94 offset:12288
	ds_read_b64 v[236:237], v94 offset:14336
	ds_read_b64 v[234:235], v95 offset:12288
	ds_read_b64 v[238:239], v95 offset:14336
	v_cvt_pk_bf16_f32 v67, v144, v145
	v_cvt_pk_bf16_f32 v68, v146, v147
	v_cvt_pk_bf16_f32 v69, v148, v151
	v_exp_f32_e32 v81, v91
	s_waitcnt lgkmcnt(0)
	v_mfma_f32_16x16x32_bf16 v[58:61], v[236:239], v[66:69], v[58:61]
	v_exp_f32_e32 v73, v149
	v_cvt_pk_bf16_f32 v70, v150, v152
	v_cvt_pk_bf16_f32 v71, v153, v191
	v_mfma_f32_16x16x32_bf16 v[38:41], v[236:239], v[74:77], v[38:41]
	ds_read_b64 v[240:241], v94 offset:16384
	ds_read_b64 v[244:245], v94 offset:18432
	ds_read_b64 v[242:243], v95 offset:16384
	ds_read_b64 v[246:247], v95 offset:18432
	v_add_u32_e32 v94, v0, v135
	v_add_u32_e32 v0, v0, v136
	v_mfma_f32_16x16x32_bf16 v[62:65], v[232:235], v[66:69], v[62:65]
	v_cvt_pk_bf16_f32 v72, v192, v193
	v_cvt_pk_bf16_f32 v73, v194, v73
	v_cvt_pk_bf16_f32 v81, v97, v81
	v_mfma_f32_16x16x32_bf16 v[46:49], v[232:235], v[74:77], v[46:49]
	s_waitcnt lgkmcnt(0)
	v_mfma_f32_16x16x32_bf16 v[50:53], v[244:247], v[66:69], v[50:53]
	ds_read_b64 v[232:233], v94 offset:12288
	ds_read_b64 v[236:237], v94 offset:14336
	s_mov_b32 s93, s92
	s_mov_b32 s94, s92
	v_mfma_f32_16x16x32_bf16 v[30:33], v[244:247], v[74:77], v[30:33]
	ds_read_b64 v[234:235], v0 offset:12288
	ds_read_b64 v[238:239], v0 offset:14336
	s_mov_b32 s95, s92
	v_mfma_f32_16x16x32_bf16 v[54:57], v[240:243], v[66:69], v[54:57]
	v_mfma_f32_16x16x32_bf16 v[34:37], v[240:243], v[74:77], v[34:37]
	s_waitcnt lgkmcnt(0)
	v_mfma_f32_16x16x32_bf16 v[58:61], v[236:239], v[70:73], v[58:61]
	v_mfma_f32_16x16x32_bf16 v[38:41], v[236:239], v[78:81], v[38:41]
	ds_read_b64 v[240:241], v94 offset:16384
	ds_read_b64 v[244:245], v94 offset:18432
	ds_read_b64 v[242:243], v0 offset:16384
	ds_read_b64 v[246:247], v0 offset:18432
	v_mfma_f32_16x16x32_bf16 v[62:65], v[232:235], v[70:73], v[62:65]
	v_mfma_f32_16x16x32_bf16 v[46:49], v[232:235], v[78:81], v[46:49]
	s_waitcnt lgkmcnt(0)
	v_mov_b64_e32 v[82:83], s[92:93]
	v_mov_b64_e32 v[84:85], s[94:95]
	v_mfma_f32_16x16x32_bf16 v[54:57], v[240:243], v[70:73], v[54:57]
	s_nop 0
	v_mfma_f32_16x16x32_bf16 v[42:45], v[82:85], v[66:69], v[42:45]
	v_mfma_f32_16x16x32_bf16 v[26:29], v[82:85], v[74:77], v[26:29]
	v_mfma_f32_16x16x32_bf16 v[34:37], v[240:243], v[78:81], v[34:37]
	v_mfma_f32_16x16x32_bf16 v[50:53], v[244:247], v[70:73], v[50:53]
	v_mfma_f32_16x16x32_bf16 v[30:33], v[244:247], v[78:81], v[30:33]
	v_mfma_f32_16x16x32_bf16 v[42:45], v[82:85], v[70:73], v[42:45]
	v_mfma_f32_16x16x32_bf16 v[26:29], v[82:85], v[78:81], v[26:29]

; template <int DK, int MODE, int RBM, class SF, class FF, class POST>
; DEVI void attn_tile_body(const bf16x8 (&qf)[2][DK / 32], const char* Ks, const char* Vs, SF& sf, FF& ff, POST& post,
;                          int cur, int c0, int c1, float (&m)[2], float (&l)[2], f32x4 (&o)[5][2], int fr, int fq) {
;     ...
;     bf16x8 pf[2][2];
; #pragma unroll
;     for (int rb = 0; rb < 2; ++rb) {
;       if (!(RBM & (1 << rb))) continue;
; #pragma unroll
;       for (int kp2 = 0; kp2 < 2; ++kp2) {
;         u32x4 w;
;         w[0] = pack2(s[2 * kp2][rb][0], s[2 * kp2][rb][1]); w[1] = pack2(s[2 * kp2][rb][2], s[2 * kp2][rb][3]);
;         w[2] = pack2(s[2 * kp2 + 1][rb][0], s[2 * kp2 + 1][rb][1]); w[3] = pack2(s[2 * kp2 + 1][rb][2], s[2 * kp2 + 1][rb][3]);
;         pf[rb][kp2] = __builtin_bit_cast(bf16x8, w);
;       }
;     }
; #pragma unroll
;     for (int kp2 = 0; kp2 < 2; ++kp2)
; #pragma unroll
;       for (int db = 0; db < 4; ++db) {
;         const char* base = Vs + (db * 16 + fr) * 128 + (fq & 1) * 8;
;         const int c = kp2 * 4 + (fq >> 1);
;         u32x2 lo = *(const u32x2*)(base + ((c ^ (fr & 7)) * 16));
;         u32x2 hi = *(const u32x2*)(base + (((c + 2) ^ (fr & 7)) * 16));
;         u32x4 w; w[0] = lo[0]; w[1] = lo[1]; w[2] = hi[0]; w[3] = hi[1];
;         bf16x8 vf = __builtin_bit_cast(bf16x8, w);
;         if (RBM & 1) o[db][0] = __builtin_amdgcn_mfma_f32_16x16x32_bf16(vf, pf[0][kp2], o[db][0], 0, 0, 0);
;         if (RBM & 2) o[db][1] = __builtin_amdgcn_mfma_f32_16x16x32_bf16(vf, pf[1][kp2], o[db][1], 0, 0, 0);
;       }
;     if (MODE == 0) {
;       u32x4 w1; w1[0] = w1[1] = w1[2] = w1[3] = 0x3F803F80u;
;       const bf16x8 ones = __builtin_bit_cast(bf16x8, w1);
; #pragma unroll
;       for (int kp2 = 0; kp2 < 2; ++kp2) {
;         if (RBM & 1) o[4][0] = __builtin_amdgcn_mfma_f32_16x16x32_bf16(ones, pf[0][kp2], o[4][0], 0, 0, 0);
;         if (RBM & 2) o[4][1] = __builtin_amdgcn_mfma_f32_16x16x32_bf16(ones, pf[1][kp2], o[4][1], 0, 0, 0);
;       }
.LBB0_1059:
	s_or_b64 exec, exec, s[38:39]
	v_add3_u32 v126, s43, v135, v132
	v_cvt_pk_bf16_f32 v64, v213, v214
	v_add_u32_e32 v127, v126, v138
	v_add_u32_e32 v213, v126, v139
	ds_read_b64 v[232:233], v127 offset:8192
	ds_read_b64 v[236:237], v127 offset:10240
	ds_read_b64 v[234:235], v213 offset:8192
	ds_read_b64 v[238:239], v213 offset:10240
	v_cvt_pk_bf16_f32 v65, v215, v216
	v_cvt_pk_bf16_f32 v66, v217, v218
	v_cvt_pk_bf16_f32 v67, v219, v220
	s_waitcnt lgkmcnt(0)
	v_exp_f32_e32 v63, v221
	v_mfma_f32_16x16x32_bf16 v[52:55], v[236:239], v[64:67], v[52:55]
	ds_read_b64 v[240:241], v127 offset:12288
	ds_read_b64 v[244:245], v127 offset:14336
	ds_read_b64 v[242:243], v213 offset:12288
	ds_read_b64 v[246:247], v213 offset:14336
	v_add_u32_e32 v127, v126, v140
	v_add_u32_e32 v126, v126, v141
	v_mfma_f32_16x16x32_bf16 v[56:59], v[232:235], v[64:67], v[56:59]
	s_waitcnt lgkmcnt(0)
	ds_read_b64 v[232:233], v127 offset:8192
	ds_read_b64 v[236:237], v127 offset:10240
	v_mfma_f32_16x16x32_bf16 v[44:47], v[244:247], v[64:67], v[44:47]
	ds_read_b64 v[234:235], v126 offset:8192
	ds_read_b64 v[238:239], v126 offset:10240
	v_cvt_pk_bf16_f32 v60, v222, v223
	v_cvt_pk_bf16_f32 v61, v224, v225
	v_mfma_f32_16x16x32_bf16 v[48:51], v[240:243], v[64:67], v[48:51]
	v_cvt_pk_bf16_f32 v62, v226, v227
	s_waitcnt lgkmcnt(0)
	v_cvt_pk_bf16_f32 v63, v228, v63
	s_nop 1
	v_mfma_f32_16x16x32_bf16 v[52:55], v[236:239], v[60:63], v[52:55]
	ds_read_b64 v[240:241], v127 offset:12288
	ds_read_b64 v[244:245], v127 offset:14336
	ds_read_b64 v[242:243], v126 offset:12288
	ds_read_b64 v[246:247], v126 offset:14336
	s_mov_b32 s93, s92
	s_mov_b32 s94, s92
	v_mfma_f32_16x16x32_bf16 v[56:59], v[232:235], v[60:63], v[56:59]
	s_waitcnt lgkmcnt(0)
	s_mov_b32 s95, s92
	v_mov_b64_e32 v[68:69], s[92:93]
	v_mov_b64_e32 v[70:71], s[94:95]
	v_mfma_f32_16x16x32_bf16 v[48:51], v[240:243], v[60:63], v[48:51]
	s_nop 0
	v_mfma_f32_16x16x32_bf16 v[36:39], v[68:71], v[64:67], v[36:39]
	v_mfma_f32_16x16x32_bf16 v[44:47], v[244:247], v[60:63], v[44:47]
	v_mfma_f32_16x16x32_bf16 v[36:39], v[68:71], v[60:63], v[36:39]

; template <int DK, int MODE, int RBM, class SF, class FF, class POST>
; DEVI void attn_tile_body(const bf16x8 (&qf)[2][DK / 32], const char* Ks, const char* Vs, SF& sf, FF& ff, POST& post,
;                          int cur, int c0, int c1, float (&m)[2], float (&l)[2], f32x4 (&o)[5][2], int fr, int fq) {
;     ...
;     bf16x8 pf[2][2];
; #pragma unroll
;     for (int rb = 0; rb < 2; ++rb) {
;       if (!(RBM & (1 << rb))) continue;
; #pragma unroll
;       for (int kp2 = 0; kp2 < 2; ++kp2) {
;         u32x4 w;
;         w[0] = pack2(s[2 * kp2][rb][0], s[2 * kp2][rb][1]); w[1] = pack2(s[2 * kp2][rb][2], s[2 * kp2][rb][3]);
;         w[2] = pack2(s[2 * kp2 + 1][rb][0], s[2 * kp2 + 1][rb][1]); w[3] = pack2(s[2 * kp2 + 1][rb][2], s[2 * kp2 + 1][rb][3]);
;         pf[rb][kp2] = __builtin_bit_cast(bf16x8, w);
;       }
;     }
; #pragma unroll
;     for (int kp2 = 0; kp2 < 2; ++kp2)
; #pragma unroll
;       for (int db = 0; db < 4; ++db) {
;         const char* base = Vs + (db * 16 + fr) * 128 + (fq & 1) * 8;
;         const int c = kp2 * 4 + (fq >> 1);
;         u32x2 lo = *(const u32x2*)(base + ((c ^ (fr & 7)) * 16));
;         u32x2 hi = *(const u32x2*)(base + (((c + 2) ^ (fr & 7)) * 16));
;         u32x4 w; w[0] = lo[0]; w[1] = lo[1]; w[2] = hi[0]; w[3] = hi[1];
;         bf16x8 vf = __builtin_bit_cast(bf16x8, w);
;         if (RBM & 1) o[db][0] = __builtin_amdgcn_mfma_f32_16x16x32_bf16(vf, pf[0][kp2], o[db][0], 0, 0, 0);
;         if (RBM & 2) o[db][1] = __builtin_amdgcn_mfma_f32_16x16x32_bf16(vf, pf[1][kp2], o[db][1], 0, 0, 0);
;       }
;     if (MODE == 0) {
;       u32x4 w1; w1[0] = w1[1] = w1[2] = w1[3] = 0x3F803F80u;
;       const bf16x8 ones = __builtin_bit_cast(bf16x8, w1);
; #pragma unroll
;       for (int kp2 = 0; kp2 < 2; ++kp2) {
;         if (RBM & 1) o[4][0] = __builtin_amdgcn_mfma_f32_16x16x32_bf16(ones, pf[0][kp2], o[4][0], 0, 0, 0);
;         if (RBM & 2) o[4][1] = __builtin_amdgcn_mfma_f32_16x16x32_bf16(ones, pf[1][kp2], o[4][1], 0, 0, 0);
;       }
.LBB0_1101:
	s_or_b64 exec, exec, s[38:39]
	v_exp_f32_e32 v2, v217
	v_cvt_pk_bf16_f32 v64, v126, v127
	v_cvt_pk_bf16_f32 v65, v211, v212
	v_cvt_pk_bf16_f32 v66, v213, v214
	v_cvt_pk_bf16_f32 v63, v224, v2
	v_add3_u32 v2, s43, v135, v132
	v_add_u32_e32 v3, v2, v138
	v_add_u32_e32 v126, v2, v139
	ds_read_b64 v[232:233], v3 offset:8192
	ds_read_b64 v[236:237], v3 offset:10240
	ds_read_b64 v[234:235], v126 offset:8192
	ds_read_b64 v[238:239], v126 offset:10240
	v_cvt_pk_bf16_f32 v67, v215, v216
	v_cvt_pk_bf16_f32 v60, v218, v219
	v_cvt_pk_bf16_f32 v61, v220, v221
	s_waitcnt lgkmcnt(0)
	v_cvt_pk_bf16_f32 v62, v222, v223
	v_mfma_f32_16x16x32_bf16 v[32:35], v[236:239], v[64:67], v[32:35]
	ds_read_b64 v[240:241], v3 offset:12288
	ds_read_b64 v[244:245], v3 offset:14336
	ds_read_b64 v[242:243], v126 offset:12288
	ds_read_b64 v[246:247], v126 offset:14336
	v_add_u32_e32 v3, v2, v140
	v_add_u32_e32 v2, v2, v141
	v_mfma_f32_16x16x32_bf16 v[40:43], v[232:235], v[64:67], v[40:43]
	s_waitcnt lgkmcnt(0)
	ds_read_b64 v[232:233], v3 offset:8192
	ds_read_b64 v[236:237], v3 offset:10240
	v_mfma_f32_16x16x32_bf16 v[24:27], v[244:247], v[64:67], v[24:27]
	ds_read_b64 v[234:235], v2 offset:8192
	ds_read_b64 v[238:239], v2 offset:10240
	s_mov_b32 s93, s92
	s_mov_b32 s94, s92
	v_mfma_f32_16x16x32_bf16 v[28:31], v[240:243], v[64:67], v[28:31]
	s_waitcnt lgkmcnt(0)
	s_mov_b32 s95, s92
	v_mfma_f32_16x16x32_bf16 v[32:35], v[236:239], v[60:63], v[32:35]
	ds_read_b64 v[240:241], v3 offset:12288
	ds_read_b64 v[244:245], v3 offset:14336
	ds_read_b64 v[242:243], v2 offset:12288
	ds_read_b64 v[246:247], v2 offset:14336
	v_mfma_f32_16x16x32_bf16 v[40:43], v[232:235], v[60:63], v[40:43]
	s_waitcnt lgkmcnt(0)
	v_mov_b64_e32 v[68:69], s[92:93]
	v_mov_b64_e32 v[70:71], s[94:95]
	v_mfma_f32_16x16x32_bf16 v[28:31], v[240:243], v[60:63], v[28:31]
	s_nop 0
	v_mfma_f32_16x16x32_bf16 v[20:23], v[68:71], v[64:67], v[20:23]
	v_mfma_f32_16x16x32_bf16 v[24:27], v[244:247], v[60:63], v[24:27]
	v_mfma_f32_16x16x32_bf16 v[20:23], v[68:71], v[60:63], v[20:23]

; template <int DK, int MODE, int RBM, class SF, class FF, class POST>
; DEVI void attn_tile_body(const bf16x8 (&qf)[2][DK / 32], const char* Ks, const char* Vs, SF& sf, FF& ff, POST& post,
;                          int cur, int c0, int c1, float (&m)[2], float (&l)[2], f32x4 (&o)[5][2], int fr, int fq) {
;     ...
;     bf16x8 pf[2][2];
; #pragma unroll
;     for (int rb = 0; rb < 2; ++rb) {
;       if (!(RBM & (1 << rb))) continue;
; #pragma unroll
;       for (int kp2 = 0; kp2 < 2; ++kp2) {
;         u32x4 w;
;         w[0] = pack2(s[2 * kp2][rb][0], s[2 * kp2][rb][1]); w[1] = pack2(s[2 * kp2][rb][2], s[2 * kp2][rb][3]);
;         w[2] = pack2(s[2 * kp2 + 1][rb][0], s[2 * kp2 + 1][rb][1]); w[3] = pack2(s[2 * kp2 + 1][rb][2], s[2 * kp2 + 1][rb][3]);
;         pf[rb][kp2] = __builtin_bit_cast(bf16x8, w);
;       }
;     }
; #pragma unroll
;     for (int kp2 = 0; kp2 < 2; ++kp2)
; #pragma unroll
;       for (int db = 0; db < 4; ++db) {
;         const char* base = Vs + (db * 16 + fr) * 128 + (fq & 1) * 8;
;         const int c = kp2 * 4 + (fq >> 1);
;         u32x2 lo = *(const u32x2*)(base + ((c ^ (fr & 7)) * 16));
;         u32x2 hi = *(const u32x2*)(base + (((c + 2) ^ (fr & 7)) * 16));
;         u32x4 w; w[0] = lo[0]; w[1] = lo[1]; w[2] = hi[0]; w[3] = hi[1];
;         bf16x8 vf = __builtin_bit_cast(bf16x8, w);
;         if (RBM & 1) o[db][0] = __builtin_amdgcn_mfma_f32_16x16x32_bf16(vf, pf[0][kp2], o[db][0], 0, 0, 0);
;         if (RBM & 2) o[db][1] = __builtin_amdgcn_mfma_f32_16x16x32_bf16(vf, pf[1][kp2], o[db][1], 0, 0, 0);
;       }
;     if (MODE == 0) {
;       u32x4 w1; w1[0] = w1[1] = w1[2] = w1[3] = 0x3F803F80u;
;       const bf16x8 ones = __builtin_bit_cast(bf16x8, w1);
; #pragma unroll
;       for (int kp2 = 0; kp2 < 2; ++kp2) {
;         if (RBM & 1) o[4][0] = __builtin_amdgcn_mfma_f32_16x16x32_bf16(ones, pf[0][kp2], o[4][0], 0, 0, 0);
;         if (RBM & 2) o[4][1] = __builtin_amdgcn_mfma_f32_16x16x32_bf16(ones, pf[1][kp2], o[4][1], 0, 0, 0);
;       }
.LBB0_1187:
	s_or_b64 exec, exec, s[38:39]
	v_exp_f32_e32 v2, v215
	v_cvt_pk_bf16_f32 v64, v126, v0
	v_add3_u32 v0, s43, v135, v132
	v_add_u32_e32 v3, v0, v139
	v_cvt_pk_bf16_f32 v63, v222, v2
	v_add_u32_e32 v2, v0, v138
	v_add_u32_e32 v2, 0x100, v2
	v_add_u32_e32 v3, 0x100, v3
	ds_read_b64 v[232:233], v2 offset:24576
	ds_read_b64 v[236:237], v2 offset:26624
	ds_read_b64 v[234:235], v3 offset:24576
	ds_read_b64 v[238:239], v3 offset:26624
	v_cvt_pk_bf16_f32 v66, v211, v212
	v_cvt_pk_bf16_f32 v67, v213, v214
	v_cvt_pk_bf16_f32 v65, v127, v210
	s_waitcnt lgkmcnt(0)
	v_cvt_pk_bf16_f32 v60, v216, v217
	v_mfma_f32_16x16x32_bf16 v[32:35], v[236:239], v[64:67], v[32:35]
	ds_read_b64 v[240:241], v2 offset:28672
	ds_read_b64 v[244:245], v2 offset:30720
	ds_read_b64 v[242:243], v3 offset:28672
	ds_read_b64 v[246:247], v3 offset:30720
	v_add_u32_e32 v2, v0, v140
	v_add_u32_e32 v0, v0, v141
	v_mfma_f32_16x16x32_bf16 v[40:43], v[232:235], v[64:67], v[40:43]
	v_add_u32_e32 v2, 0x100, v2
	s_waitcnt lgkmcnt(0)
	v_add_u32_e32 v0, 0x100, v0
	v_mfma_f32_16x16x32_bf16 v[24:27], v[244:247], v[64:67], v[24:27]
	ds_read_b64 v[232:233], v2 offset:24576
	ds_read_b64 v[236:237], v2 offset:26624
	ds_read_b64 v[234:235], v0 offset:24576
	ds_read_b64 v[238:239], v0 offset:26624
	v_cvt_pk_bf16_f32 v61, v218, v219
	v_mfma_f32_16x16x32_bf16 v[28:31], v[240:243], v[64:67], v[28:31]
	v_cvt_pk_bf16_f32 v62, v220, v221
	s_waitcnt lgkmcnt(0)
	s_mov_b32 s93, s92
	v_mfma_f32_16x16x32_bf16 v[32:35], v[236:239], v[60:63], v[32:35]
	ds_read_b64 v[240:241], v2 offset:28672
	ds_read_b64 v[244:245], v2 offset:30720
	ds_read_b64 v[242:243], v0 offset:28672
	ds_read_b64 v[246:247], v0 offset:30720
	s_mov_b32 s94, s92
	s_mov_b32 s95, s92
	v_mfma_f32_16x16x32_bf16 v[40:43], v[232:235], v[60:63], v[40:43]
	s_waitcnt lgkmcnt(0)
	v_mov_b64_e32 v[68:69], s[92:93]
	v_mov_b64_e32 v[70:71], s[94:95]
	v_mfma_f32_16x16x32_bf16 v[28:31], v[240:243], v[60:63], v[28:31]
	s_nop 0
	v_mfma_f32_16x16x32_bf16 v[20:23], v[68:71], v[64:67], v[20:23]
	v_mfma_f32_16x16x32_bf16 v[24:27], v[244:247], v[60:63], v[24:27]
	v_mfma_f32_16x16x32_bf16 v[20:23], v[68:71], v[60:63], v[20:23]

; template <int DK, int MODE, int RBM, class SF, class FF, class POST>
; DEVI void attn_tile_body(const bf16x8 (&qf)[2][DK / 32], const char* Ks, const char* Vs, SF& sf, FF& ff, POST& post,
;                          int cur, int c0, int c1, float (&m)[2], float (&l)[2], f32x4 (&o)[5][2], int fr, int fq) {
;     ...
;     bf16x8 pf[2][2];
; #pragma unroll
;     for (int rb = 0; rb < 2; ++rb) {
;       if (!(RBM & (1 << rb))) continue;
; #pragma unroll
;       for (int kp2 = 0; kp2 < 2; ++kp2) {
;         u32x4 w;
;         w[0] = pack2(s[2 * kp2][rb][0], s[2 * kp2][rb][1]); w[1] = pack2(s[2 * kp2][rb][2], s[2 * kp2][rb][3]);
;         w[2] = pack2(s[2 * kp2 + 1][rb][0], s[2 * kp2 + 1][rb][1]); w[3] = pack2(s[2 * kp2 + 1][rb][2], s[2 * kp2 + 1][rb][3]);
;         pf[rb][kp2] = __builtin_bit_cast(bf16x8, w);
;       }
;     }
; #pragma unroll
;     for (int kp2 = 0; kp2 < 2; ++kp2)
; #pragma unroll
;       for (int db = 0; db < 4; ++db) {
;         const char* base = Vs + (db * 16 + fr) * 128 + (fq & 1) * 8;
;         const int c = kp2 * 4 + (fq >> 1);
;         u32x2 lo = *(const u32x2*)(base + ((c ^ (fr & 7)) * 16));
;         u32x2 hi = *(const u32x2*)(base + (((c + 2) ^ (fr & 7)) * 16));
;         u32x4 w; w[0] = lo[0]; w[1] = lo[1]; w[2] = hi[0]; w[3] = hi[1];
;         bf16x8 vf = __builtin_bit_cast(bf16x8, w);
;         if (RBM & 1) o[db][0] = __builtin_amdgcn_mfma_f32_16x16x32_bf16(vf, pf[0][kp2], o[db][0], 0, 0, 0);
;         if (RBM & 2) o[db][1] = __builtin_amdgcn_mfma_f32_16x16x32_bf16(vf, pf[1][kp2], o[db][1], 0, 0, 0);
;       }
;     if (MODE == 0) {
;       u32x4 w1; w1[0] = w1[1] = w1[2] = w1[3] = 0x3F803F80u;
;       const bf16x8 ones = __builtin_bit_cast(bf16x8, w1);
; #pragma unroll
;       for (int kp2 = 0; kp2 < 2; ++kp2) {
;         if (RBM & 1) o[4][0] = __builtin_amdgcn_mfma_f32_16x16x32_bf16(ones, pf[0][kp2], o[4][0], 0, 0, 0);
;         if (RBM & 2) o[4][1] = __builtin_amdgcn_mfma_f32_16x16x32_bf16(ones, pf[1][kp2], o[4][1], 0, 0, 0);
;       }
.LBB0_1289:
	s_or_b64 exec, exec, s[38:39]
	v_cvt_pk_bf16_f32 v73, v87, v88
	v_add3_u32 v88, s42, v145, v142
	v_cvt_pk_bf16_f32 v74, v89, v90
	v_add_u32_e32 v89, v88, v146
	v_add_u32_e32 v90, v88, v147
	v_cvt_pk_bf16_f32 v68, v77, v76
	v_cvt_pk_bf16_f32 v69, v78, v79
	v_cvt_pk_bf16_f32 v70, v80, v81
	v_cvt_pk_bf16_f32 v71, v82, v84
	v_cvt_pk_bf16_f32 v72, v83, v86
	ds_read_b64 v[232:233], v89 offset:8192
	ds_read_b64 v[236:237], v89 offset:10240
	ds_read_b64 v[234:235], v90 offset:8192
	ds_read_b64 v[238:239], v90 offset:10240
	v_cvt_pk_bf16_f32 v60, v214, v215
	v_cvt_pk_bf16_f32 v61, v216, v217
	v_cvt_pk_bf16_f32 v62, v218, v219
	v_cvt_pk_bf16_f32 v63, v220, v223
	s_waitcnt lgkmcnt(0)
	v_exp_f32_e32 v75, v85
	v_mfma_f32_16x16x32_bf16 v[48:51], v[236:239], v[60:63], v[48:51]
	v_exp_f32_e32 v67, v221
	v_cvt_pk_bf16_f32 v64, v222, v224
	v_cvt_pk_bf16_f32 v65, v225, v226
	v_mfma_f32_16x16x32_bf16 v[40:43], v[236:239], v[68:71], v[40:43]
	ds_read_b64 v[240:241], v89 offset:12288
	ds_read_b64 v[244:245], v89 offset:14336
	ds_read_b64 v[242:243], v90 offset:12288
	ds_read_b64 v[246:247], v90 offset:14336
	v_add_u32_e32 v89, v88, v148
	v_add_u32_e32 v88, v88, v149
	v_mfma_f32_16x16x32_bf16 v[52:55], v[232:235], v[60:63], v[52:55]
	v_cvt_pk_bf16_f32 v66, v227, v228
	v_cvt_pk_bf16_f32 v67, v229, v67
	v_cvt_pk_bf16_f32 v75, v91, v75
	v_mfma_f32_16x16x32_bf16 v[32:35], v[232:235], v[68:71], v[32:35]
	s_waitcnt lgkmcnt(0)
	v_mfma_f32_16x16x32_bf16 v[44:47], v[244:247], v[60:63], v[44:47]
	ds_read_b64 v[232:233], v89 offset:8192
	ds_read_b64 v[236:237], v89 offset:10240
	s_mov_b32 s93, s92
	s_mov_b32 s94, s92
	v_mfma_f32_16x16x32_bf16 v[28:31], v[244:247], v[68:71], v[28:31]
	ds_read_b64 v[234:235], v88 offset:8192
	ds_read_b64 v[238:239], v88 offset:10240
	s_mov_b32 s95, s92
	v_mfma_f32_16x16x32_bf16 v[56:59], v[240:243], v[60:63], v[56:59]
	v_mfma_f32_16x16x32_bf16 v[36:39], v[240:243], v[68:71], v[36:39]
	s_waitcnt lgkmcnt(0)
	v_mfma_f32_16x16x32_bf16 v[48:51], v[236:239], v[64:67], v[48:51]
	v_mfma_f32_16x16x32_bf16 v[40:43], v[236:239], v[72:75], v[40:43]
	ds_read_b64 v[240:241], v89 offset:12288
	ds_read_b64 v[244:245], v89 offset:14336
	ds_read_b64 v[242:243], v88 offset:12288
	ds_read_b64 v[246:247], v88 offset:14336
	v_mfma_f32_16x16x32_bf16 v[52:55], v[232:235], v[64:67], v[52:55]
	v_mfma_f32_16x16x32_bf16 v[32:35], v[232:235], v[72:75], v[32:35]
	s_waitcnt lgkmcnt(0)
	v_mov_b64_e32 v[76:77], s[92:93]
	v_mov_b64_e32 v[78:79], s[94:95]
	v_mfma_f32_16x16x32_bf16 v[56:59], v[240:243], v[64:67], v[56:59]
	s_nop 0
	v_mfma_f32_16x16x32_bf16 v[24:27], v[76:79], v[60:63], v[24:27]
	v_mfma_f32_16x16x32_bf16 v[20:23], v[76:79], v[68:71], v[20:23]
	v_mfma_f32_16x16x32_bf16 v[36:39], v[240:243], v[72:75], v[36:39]
	v_mfma_f32_16x16x32_bf16 v[44:47], v[244:247], v[64:67], v[44:47]
	v_mfma_f32_16x16x32_bf16 v[28:31], v[244:247], v[72:75], v[28:31]
	v_mfma_f32_16x16x32_bf16 v[24:27], v[76:79], v[64:67], v[24:27]
	v_mfma_f32_16x16x32_bf16 v[20:23], v[76:79], v[72:75], v[20:23]
